# merge GEMM: first four LDS-DMA stage pairs issued at the start of the preceding grid seam (overlap store drain + barrier wait)
# speedup vs baseline: 1.0037x; 1.0013x over previous
; #define PG8_STAGE2(bufoff, gbase, r2, Ksel) do { \
;         __builtin_amdgcn_global_load_lds((const unsigned*)((const char*)(gbase) + ((r2)[0] * (Ksel) + cb2[0])), (LAS unsigned*)(lds + (bufoff) + ldsw), 16, 0, 0); \
;         __builtin_amdgcn_global_load_lds((const unsigned*)((const char*)(gbase) + ((r2)[1] * (Ksel) + cb2[1])), (LAS unsigned*)(lds + (bufoff) + ldsw + 8192), 16, 0, 0); } while (0)
;     __device__ bool next(int i, Unit& u) const {
;         const long L = (long)i * G + c; if (L >= nwg) return false;
;         int wgid = (int)L; { const int q = nwg / NXCD, r = nwg % NXCD, xcd = wgid % NXCD, off = wgid / NXCD; wgid = (xcd < r ? xcd * (q + 1) : r * (q + 1) + (xcd - r) * q) + off; }
;         const int nig = WGM * nN, gid = wgid / nig, fm = gid * WGM, gsz = (nM - fm) < WGM ? (nM - fm) : WGM;
;         u.pm = fm + ((wgid % nig) % gsz); u.pn = (wgid % nig) / gsz; return true;
; template <class EpiMid, class EpiEnd>
; __device__ __forceinline__ void gemm_phase2(LAS unsigned char* lds, const Gemm g0, const Gemm g1, const StaticOrder& S, const EpiMid& Emid, const EpiEnd& Eend) {
;     ...
;     const char* cA = (const char*)g0.A + (size_t)cur.pm * 2 * hstep0; const char* cB = (const char*)g0.Bt + (size_t)cur.pn * 2 * hstep0;
;     PG8_STAGE2(PG8_SB(0, 0), cB, rB2, K0); PG8_STAGE2(PG8_SA(0, 0), cA, rA2, K0);
;     PG8_STAGE2(PG8_SB(0, 1), cB + hstep0, rB2, K0); PG8_STAGE2(PG8_SA(0, 1), cA + hstep0, rA2, K0);
.LBB0_703:
	s_mov_b32 s101, 0
	s_cmp_gt_i32 s91, 7
	s_cselect_b64 s[0:1], -1, 0
	s_and_b64 s[2:3], s[8:9], s[0:1]
	s_andn2_b64 vcc, exec, s[2:3]
	s_cbranch_vccnz .LBB0_753
	s_cmp_eq_u32 s99, 1
	s_cbranch_scc0 .Lp7e_skip
	s_cmpk_gt_i32 s84, 0xff
	s_cbranch_scc1 .Lp7e_skip
	s_mov_b32 s101, 1
	v_readfirstlane_b32 s30, v212
	s_ashr_i32 s31, s84, 31
	s_lshr_b32 s2, s31, 29
	s_add_i32 s5, s84, s2
	s_and_b32 s2, s5, -8
	s_sub_i32 s8, s84, s2
	s_cmp_gt_i32 s8, -1
	s_cbranch_scc0 .Lp7e_757
	s_lshl_b32 s4, s8, 5
	s_cbranch_execz .Lp7e_758
	s_branch .Lp7e_759

; #define PG8_STAGE2(bufoff, gbase, r2, Ksel) do { \
;         __builtin_amdgcn_global_load_lds((const unsigned*)((const char*)(gbase) + ((r2)[0] * (Ksel) + cb2[0])), (LAS unsigned*)(lds + (bufoff) + ldsw), 16, 0, 0); \
;         __builtin_amdgcn_global_load_lds((const unsigned*)((const char*)(gbase) + ((r2)[1] * (Ksel) + cb2[1])), (LAS unsigned*)(lds + (bufoff) + ldsw + 8192), 16, 0, 0); } while (0)
; template <class EpiMid, class EpiEnd>
; __device__ __forceinline__ void gemm_phase2(LAS unsigned char* lds, const Gemm g0, const Gemm g1, const StaticOrder& S, const EpiMid& Emid, const EpiEnd& Eend) {
;     const int tid = threadIdx.x, wid = __builtin_amdgcn_readfirstlane(tid >> 6), lane = tid & 63, wr = wid >> 2, wc = wid & 3, fr = lane & 15, fq = lane >> 4;
;     unsigned rA2[2], rB2[2], cb2[2];
; #pragma unroll
;     for (int i = 0; i < 2; ++i) { int R, C; stage_rc(tid * 16 + i * 8192, R, C); const int Rb = (R & ~31) + perm32(R & 31); rA2[i] = (unsigned)R * 2u; rB2[i] = (unsigned)Rb * 2u; cb2[i] = (unsigned)C * 2u; }
;     const size_t kstep = (size_t)(BK * 2);
;     const unsigned K0 = (unsigned)g0.K, K1 = (unsigned)g1.K;
;     const size_t hstep0 = (size_t)HALF * g0.K * 2, hstep1 = (size_t)HALF * g1.K * 2;
;     const unsigned ldsw = (unsigned)wid * 1024u;
;     const int aoff = lds_byte(wr * 64 + fr, fq * 8), boff = lds_byte(wc * 32 + fr, fq * 8);
;     ...
;     const char* cA = (const char*)g0.A + (size_t)cur.pm * 2 * hstep0; const char* cB = (const char*)g0.Bt + (size_t)cur.pn * 2 * hstep0;
;     PG8_STAGE2(PG8_SB(0, 0), cB, rB2, K0); PG8_STAGE2(PG8_SA(0, 0), cA, rA2, K0);
;     PG8_STAGE2(PG8_SB(0, 1), cB + hstep0, rB2, K0); PG8_STAGE2(PG8_SA(0, 1), cA + hstep0, rA2, K0);
.Lp7e_759:
	s_ashr_i32 s2, s5, 3
	s_add_u32 s34, s88, 0x1800000
	s_addc_u32 s35, s89, 0
	s_add_i32 s2, s4, s2
	s_ashr_i32 s4, s2, 31
	s_lshr_b32 s4, s4, 28
	s_add_i32 s4, s2, s4
	s_ashr_i32 s5, s4, 4
	s_and_b32 s4, s4, -16
	s_sub_i32 s4, s2, s4
	s_bfe_i32 s2, s4, 0x80000
	v_lshlrev_b32_e32 v0, 4, v212
	v_and_b32_e32 v1, 32, v212
	s_bfe_u32 s2, s2, 0x2000d
	v_bitop3_b32 v12, v0, v1, 48 bitop3:0x6c
	v_lshrrev_b32_e32 v1, 1, v212
	v_lshrrev_b32_e32 v3, 5, v212
	s_add_i32 s9, s4, s2
	v_and_b32_e32 v1, 24, v1
	v_and_b32_e32 v3, 4, v3
	v_bfe_u32 v4, v212, 2, 2
	s_bfe_i32 s2, s9, 0x80000
	s_and_b32 s9, s9, 0xfc
	v_bfe_u32 v2, v212, 2, 4
	v_or3_b32 v1, v3, v4, v1
	v_lshrrev_b32_e32 v3, 3, v212
	s_movk_i32 s3, 0x70
	s_sub_i32 s4, s4, s9
	v_and_or_b32 v14, v3, s3, v2
	s_movk_i32 s3, 0x60
	v_add_u32_e32 v0, 0x2000, v0
	s_lshl_b32 s5, s5, 2
	s_sext_i32_i8 s4, s4
	v_and_or_b32 v15, v3, s3, v1
	v_lshrrev_b32_e32 v0, 7, v0
	s_movk_i32 s3, 0xf0
	s_add_i32 s18, s5, s4
	s_lshr_b32 s8, s30, 6
	v_and_or_b32 v16, v0, s3, v2
	s_movk_i32 s3, 0xe0
	s_sext_i32_i16 s2, s2
	s_ashr_i32 s19, s18, 31
	v_and_or_b32 v17, v0, s3, v1
	s_lshr_b32 s3, s30, 8
	s_lshl_b32 s33, s8, 10
	s_lshr_b32 s2, s2, 2
	s_lshl_b64 s[4:5], s[18:19], 19
	v_readlane_b32 s10, v254, 23
	v_readlane_b32 s11, v254, 24
	s_add_u32 s20, s10, s4
	s_addc_u32 s21, s11, s5
	s_bfe_i64 s[4:5], s[2:3], 0x100000
	s_lshl_b64 s[4:5], s[4:5], 19
	v_and_b32_e32 v13, 64, v212
	s_add_u32 s24, s34, s4
	v_or_b32_e32 v154, v12, v13
	s_addc_u32 s25, s35, s5
	s_add_i32 s36, s33, 0
	v_lshl_or_b32 v0, v15, 11, v154
	s_add_i32 m0, s36, 0x10000
	v_lshl_or_b32 v2, v17, 11, v154
	global_load_lds_dwordx4 v0, s[24:25]
	s_add_i32 m0, s36, 0x12000
	v_lshl_or_b32 v4, v14, 11, v154
	global_load_lds_dwordx4 v2, s[24:25]
	s_mov_b32 m0, s36
	s_add_i32 s37, s36, 0x2000
	global_load_lds_dwordx4 v4, s[20:21]
	v_lshl_or_b32 v18, v16, 11, v154
	s_mov_b32 m0, s37
	s_add_u32 s4, s24, 0x40000
	global_load_lds_dwordx4 v18, s[20:21]
	s_addc_u32 s5, s25, 0
	s_add_i32 m0, s36, 0x14000
	v_mov_b32_e32 v1, 0
	global_load_lds_dwordx4 v0, s[4:5]
	s_add_i32 m0, s36, 0x16000
	v_mov_b32_e32 v3, v1
	global_load_lds_dwordx4 v2, s[4:5]
	s_add_u32 s4, s20, 0x40000
	s_addc_u32 s5, s21, 0
	s_add_i32 s38, s36, 0x4000
	s_mov_b32 m0, s38
	s_add_i32 s39, s36, 0x6000
	global_load_lds_dwordx4 v4, s[4:5]
	s_mov_b32 m0, s39
	v_mov_b32_e32 v5, v1
	global_load_lds_dwordx4 v18, s[4:5]
.Lp7e_skip:
	s_waitcnt vmcnt(0)
	s_waitcnt vmcnt(0) lgkmcnt(0)
	s_barrier
	s_mov_b64 s[2:3], exec
	v_readlane_b32 s4, v254, 1
	v_readlane_b32 s5, v254, 2
	s_and_b64 s[4:5], s[2:3], s[4:5]
	s_mov_b64 exec, s[4:5]
	s_cbranch_execz .LBB0_752
	v_readlane_b32 s4, v254, 22
	s_waitcnt vmcnt(0) expcnt(0) lgkmcnt(0)
	s_nop 0
	v_mov_b32_e32 v0, s4
	ds_read_b32 v2, v0
	ds_read_b32 v0, v0 offset:4
	s_waitcnt lgkmcnt(1)
	v_cmp_ne_u32_e32 vcc, 0, v2
	s_cbranch_vccnz .LBB0_720
	v_readlane_b32 s4, v254, 0
	s_mul_i32 s33, s83, s4
	s_add_u32 s4, s88, 0xffc0200
	s_addc_u32 s5, s89, 0
	s_add_u32 s8, s88, 0xffc0400
	s_addc_u32 s9, s89, 0
	s_add_u32 s10, s88, 0xffc0500
	s_addc_u32 s11, s89, 0
	s_add_u32 s12, s88, 0xffc0600
	s_addc_u32 s13, s89, 0
	s_add_u32 s14, s88, 0xffc0700
	s_addc_u32 s15, s89, 0
	s_add_u32 s16, s88, 0xffc0800
	s_addc_u32 s17, s89, 0
	s_add_u32 s18, s88, 0xffc0900
	s_addc_u32 s19, s89, 0
	s_add_u32 s20, s88, 0xffc0a00
	s_addc_u32 s21, s89, 0
	s_add_u32 s22, s88, 0xffc0b00
	s_addc_u32 s23, s89, 0
	s_add_u32 s24, s88, 0xffc0c00
	s_addc_u32 s25, s89, 0
	s_add_u32 s26, s88, 0xffc0d00
	s_addc_u32 s27, s89, 0
	s_add_u32 s28, s88, 0xffc0e00
	s_addc_u32 s29, s89, 0
	s_add_u32 s30, s88, 0xffc0f00
	s_addc_u32 s31, s89, 0
	s_add_u32 s34, s88, 0xffc1000
	s_addc_u32 s35, s89, 0
	s_add_u32 s36, s88, 0xffc1100
	s_addc_u32 s37, s89, 0
	s_add_u32 s38, s88, 0xffc1200
	s_addc_u32 s39, s89, 0
	s_add_u32 s40, s88, 0xffc1300
	s_mul_i32 s33, s33, s82
	s_addc_u32 s41, s89, 0
	s_mov_b32 s48, 1
	v_mov_b32_e32 v16, 0
	s_branch .LBB0_708

; #define PG8_STAGE2(bufoff, gbase, r2, Ksel) do { \
;         __builtin_amdgcn_global_load_lds((const unsigned*)((const char*)(gbase) + ((r2)[0] * (Ksel) + cb2[0])), (LAS unsigned*)(lds + (bufoff) + ldsw), 16, 0, 0); \
;         __builtin_amdgcn_global_load_lds((const unsigned*)((const char*)(gbase) + ((r2)[1] * (Ksel) + cb2[1])), (LAS unsigned*)(lds + (bufoff) + ldsw + 8192), 16, 0, 0); } while (0)
; template <class EpiMid, class EpiEnd>
; __device__ __forceinline__ void gemm_phase2(LAS unsigned char* lds, const Gemm g0, const Gemm g1, const StaticOrder& S, const EpiMid& Emid, const EpiEnd& Eend) {
;     ...
;     Unit cur, nxt; int ui = 0;
;     if (!S.next(0, cur)) return;
;     f32x4 acc[2][2][4][2];
; #pragma unroll
;     for (int a = 0; a < 2; ++a)
; #pragma unroll
;         for (int b = 0; b < 2; ++b)
; #pragma unroll
;             for (int m = 0; m < 4; ++m)
; #pragma unroll
;                 for (int n = 0; n < 2; ++n) acc[a][b][m][n] = (f32x4){0.f, 0.f, 0.f, 0.f};
;     bf16x8 At[4][2], B0[2][2], B1[2][2];
;     const char* cA = (const char*)g0.A + (size_t)cur.pm * 2 * hstep0; const char* cB = (const char*)g0.Bt + (size_t)cur.pn * 2 * hstep0;
;     PG8_STAGE2(PG8_SB(0, 0), cB, rB2, K0); PG8_STAGE2(PG8_SA(0, 0), cA, rA2, K0);
;     PG8_STAGE2(PG8_SB(0, 1), cB + hstep0, rB2, K0); PG8_STAGE2(PG8_SA(0, 1), cA + hstep0, rA2, K0);
.LBB0_753:
	s_cmp_lt_i32 s90, 8
	s_cselect_b64 s[2:3], -1, 0
	s_and_b64 s[0:1], s[2:3], s[0:1]
	s_andn2_b64 vcc, exec, s[0:1]
	s_cbranch_vccnz .LBB0_780
	s_cmpk_gt_i32 s84, 0xff
	v_readfirstlane_b32 s30, v212
	s_cbranch_scc1 .LBB0_780
	s_cmp_eq_u32 s101, 1
	s_cbranch_scc1 .Lp7n_start
	s_ashr_i32 s31, s84, 31
	s_lshr_b32 s2, s31, 29
	s_add_i32 s5, s84, s2
	s_and_b32 s2, s5, -8
	s_sub_i32 s8, s84, s2
	s_cmp_gt_i32 s8, -1
	s_cbranch_scc0 .LBB0_757
	s_lshl_b32 s4, s8, 5
	s_cbranch_execz .LBB0_758
	s_branch .LBB0_759

; #define PG8_STAGE2(bufoff, gbase, r2, Ksel) do { \
;         __builtin_amdgcn_global_load_lds((const unsigned*)((const char*)(gbase) + ((r2)[0] * (Ksel) + cb2[0])), (LAS unsigned*)(lds + (bufoff) + ldsw), 16, 0, 0); \
;         __builtin_amdgcn_global_load_lds((const unsigned*)((const char*)(gbase) + ((r2)[1] * (Ksel) + cb2[1])), (LAS unsigned*)(lds + (bufoff) + ldsw + 8192), 16, 0, 0); } while (0)
;     __device__ bool next(int i, Unit& u) const {
;         const long L = (long)i * G + c; if (L >= nwg) return false;
;         int wgid = (int)L; { const int q = nwg / NXCD, r = nwg % NXCD, xcd = wgid % NXCD, off = wgid / NXCD; wgid = (xcd < r ? xcd * (q + 1) : r * (q + 1) + (xcd - r) * q) + off; }
;         const int nig = WGM * nN, gid = wgid / nig, fm = gid * WGM, gsz = (nM - fm) < WGM ? (nM - fm) : WGM;
;         u.pm = fm + ((wgid % nig) % gsz); u.pn = (wgid % nig) / gsz; return true;
; template <class EpiMid, class EpiEnd>
; __device__ __forceinline__ void gemm_phase2(LAS unsigned char* lds, const Gemm g0, const Gemm g1, const StaticOrder& S, const EpiMid& Emid, const EpiEnd& Eend) {
;     ...
;     const char* cA = (const char*)g0.A + (size_t)cur.pm * 2 * hstep0; const char* cB = (const char*)g0.Bt + (size_t)cur.pn * 2 * hstep0;
;     PG8_STAGE2(PG8_SB(0, 0), cB, rB2, K0); PG8_STAGE2(PG8_SA(0, 0), cA, rA2, K0);
;     PG8_STAGE2(PG8_SB(0, 1), cB + hstep0, rB2, K0); PG8_STAGE2(PG8_SA(0, 1), cA + hstep0, rA2, K0);
.LBB0_759:
	s_ashr_i32 s2, s5, 3
	s_add_u32 s34, s88, 0x1800000
	s_addc_u32 s35, s89, 0
	s_add_i32 s2, s4, s2
	s_ashr_i32 s4, s2, 31
	s_lshr_b32 s4, s4, 28
	s_add_i32 s4, s2, s4
	s_ashr_i32 s5, s4, 4
	s_and_b32 s4, s4, -16
	s_sub_i32 s4, s2, s4
	s_bfe_i32 s2, s4, 0x80000
	s_waitcnt vmcnt(0)
	v_lshlrev_b32_e32 v0, 4, v212
	v_and_b32_e32 v1, 32, v212
	s_bfe_u32 s2, s2, 0x2000d
	v_bitop3_b32 v12, v0, v1, 48 bitop3:0x6c
	v_lshrrev_b32_e32 v1, 1, v212
	v_lshrrev_b32_e32 v3, 5, v212
	s_add_i32 s9, s4, s2
	v_and_b32_e32 v1, 24, v1
	v_and_b32_e32 v3, 4, v3
	v_bfe_u32 v4, v212, 2, 2
	s_bfe_i32 s2, s9, 0x80000
	s_and_b32 s9, s9, 0xfc
	v_bfe_u32 v2, v212, 2, 4
	v_or3_b32 v1, v3, v4, v1
	v_lshrrev_b32_e32 v3, 3, v212
	s_movk_i32 s3, 0x70
	s_sub_i32 s4, s4, s9
	v_and_or_b32 v14, v3, s3, v2
	s_movk_i32 s3, 0x60
	v_add_u32_e32 v0, 0x2000, v0
	s_lshl_b32 s5, s5, 2
	s_sext_i32_i8 s4, s4
	v_and_or_b32 v15, v3, s3, v1
	v_lshrrev_b32_e32 v0, 7, v0
	s_movk_i32 s3, 0xf0
	s_add_i32 s18, s5, s4
	s_lshr_b32 s8, s30, 6
	v_and_or_b32 v16, v0, s3, v2
	s_movk_i32 s3, 0xe0
	s_sext_i32_i16 s2, s2
	s_ashr_i32 s19, s18, 31
	v_and_or_b32 v17, v0, s3, v1
	s_lshr_b32 s3, s30, 8
	s_lshl_b32 s33, s8, 10
	s_lshr_b32 s2, s2, 2
	s_lshl_b64 s[4:5], s[18:19], 19
	v_readlane_b32 s10, v254, 23
	v_readlane_b32 s11, v254, 24
	s_add_u32 s20, s10, s4
	s_addc_u32 s21, s11, s5
	s_bfe_i64 s[4:5], s[2:3], 0x100000
	s_lshl_b64 s[4:5], s[4:5], 19
	v_and_b32_e32 v13, 64, v212
	s_add_u32 s24, s34, s4
	v_or_b32_e32 v154, v12, v13
	s_addc_u32 s25, s35, s5
	s_add_i32 s36, s33, 0
	v_lshl_or_b32 v0, v15, 11, v154
	s_add_i32 m0, s36, 0x10000
	v_lshl_or_b32 v2, v17, 11, v154
	global_load_lds_dwordx4 v0, s[24:25]
	s_add_i32 m0, s36, 0x12000
	v_lshl_or_b32 v4, v14, 11, v154
	global_load_lds_dwordx4 v2, s[24:25]
	s_mov_b32 m0, s36
	s_add_i32 s37, s36, 0x2000
	global_load_lds_dwordx4 v4, s[20:21]
	v_lshl_or_b32 v18, v16, 11, v154
	s_mov_b32 m0, s37
	s_add_u32 s4, s24, 0x40000
	global_load_lds_dwordx4 v18, s[20:21]
	s_addc_u32 s5, s25, 0
	s_add_i32 m0, s36, 0x14000
	v_mov_b32_e32 v1, 0
	global_load_lds_dwordx4 v0, s[4:5]
	s_add_i32 m0, s36, 0x16000
	v_mov_b32_e32 v3, v1
	global_load_lds_dwordx4 v2, s[4:5]
	s_add_u32 s4, s20, 0x40000
	s_addc_u32 s5, s21, 0
	s_add_i32 s38, s36, 0x4000
	s_mov_b32 m0, s38
	s_add_i32 s39, s36, 0x6000
	global_load_lds_dwordx4 v4, s[4:5]
	s_mov_b32 m0, s39
	v_mov_b32_e32 v5, v1
	global_load_lds_dwordx4 v18, s[4:5]
	s_branch .Lp7n_join
.Lp7n_start:
	s_ashr_i32 s31, s84, 31
	s_lshr_b32 s2, s31, 29
	s_add_i32 s5, s84, s2
	s_and_b32 s2, s5, -8
	s_sub_i32 s8, s84, s2
	s_cmp_gt_i32 s8, -1
	s_cbranch_scc0 .Lp7n_757
	s_lshl_b32 s4, s8, 5
	s_cbranch_execz .Lp7n_758
	s_branch .Lp7n_759

; #define PG8_WAIT_V(n) asm volatile("s_waitcnt vmcnt(" #n ")" ::: "memory")
; #define PG8_BAR __builtin_amdgcn_s_barrier()
; #define PG8_STAGE2(bufoff, gbase, r2, Ksel) do { \
;         __builtin_amdgcn_global_load_lds((const unsigned*)((const char*)(gbase) + ((r2)[0] * (Ksel) + cb2[0])), (LAS unsigned*)(lds + (bufoff) + ldsw), 16, 0, 0); \
;         __builtin_amdgcn_global_load_lds((const unsigned*)((const char*)(gbase) + ((r2)[1] * (Ksel) + cb2[1])), (LAS unsigned*)(lds + (bufoff) + ldsw + 8192), 16, 0, 0); } while (0)
; #define PG8_WAIT_V(n) asm volatile("s_waitcnt vmcnt(" #n ")" ::: "memory")
; #define PG8_BAR __builtin_amdgcn_s_barrier()
; template <class EpiMid, class EpiEnd>
; __device__ __forceinline__ void gemm_phase2(LAS unsigned char* lds, const Gemm g0, const Gemm g1, const StaticOrder& S, const EpiMid& Emid, const EpiEnd& Eend) {
;     ...
;     const char* cA = (const char*)g0.A + (size_t)cur.pm * 2 * hstep0; const char* cB = (const char*)g0.Bt + (size_t)cur.pn * 2 * hstep0;
;     PG8_STAGE2(PG8_SB(0, 0), cB, rB2, K0); PG8_STAGE2(PG8_SA(0, 0), cA, rA2, K0);
;     PG8_STAGE2(PG8_SB(0, 1), cB + hstep0, rB2, K0); PG8_STAGE2(PG8_SA(0, 1), cA + hstep0, rA2, K0);
;     if (wr == 1) PG8_BAR;
;     PG8_WAIT_V(4); PG8_BAR;
;     PG8_STAGE2(PG8_SB(1, 0), cB + kstep, rB2, K0); PG8_STAGE2(PG8_SA(1, 0), cA + kstep, rA2, K0); PG8_STAGE2(PG8_SB(1, 1), cB + hstep0 + kstep, rB2, K0);
.Lp7n_759:
	s_ashr_i32 s2, s5, 3
	s_add_u32 s34, s88, 0x1800000
	s_addc_u32 s35, s89, 0
	s_add_i32 s2, s4, s2
	s_ashr_i32 s4, s2, 31
	s_lshr_b32 s4, s4, 28
	s_add_i32 s4, s2, s4
	s_ashr_i32 s5, s4, 4
	s_and_b32 s4, s4, -16
	s_sub_i32 s4, s2, s4
	s_bfe_i32 s2, s4, 0x80000
	s_waitcnt vmcnt(0)
	v_lshlrev_b32_e32 v0, 4, v212
	v_and_b32_e32 v1, 32, v212
	s_bfe_u32 s2, s2, 0x2000d
	v_bitop3_b32 v12, v0, v1, 48 bitop3:0x6c
	v_lshrrev_b32_e32 v1, 1, v212
	v_lshrrev_b32_e32 v3, 5, v212
	s_add_i32 s9, s4, s2
	v_and_b32_e32 v1, 24, v1
	v_and_b32_e32 v3, 4, v3
	v_bfe_u32 v4, v212, 2, 2
	s_bfe_i32 s2, s9, 0x80000
	s_and_b32 s9, s9, 0xfc
	v_bfe_u32 v2, v212, 2, 4
	v_or3_b32 v1, v3, v4, v1
	v_lshrrev_b32_e32 v3, 3, v212
	s_movk_i32 s3, 0x70
	s_sub_i32 s4, s4, s9
	v_and_or_b32 v14, v3, s3, v2
	s_movk_i32 s3, 0x60
	v_add_u32_e32 v0, 0x2000, v0
	s_lshl_b32 s5, s5, 2
	s_sext_i32_i8 s4, s4
	v_and_or_b32 v15, v3, s3, v1
	v_lshrrev_b32_e32 v0, 7, v0
	s_movk_i32 s3, 0xf0
	s_add_i32 s18, s5, s4
	s_lshr_b32 s8, s30, 6
	v_and_or_b32 v16, v0, s3, v2
	s_movk_i32 s3, 0xe0
	s_sext_i32_i16 s2, s2
	s_ashr_i32 s19, s18, 31
	v_and_or_b32 v17, v0, s3, v1
	s_lshr_b32 s3, s30, 8
	s_lshl_b32 s33, s8, 10
	s_lshr_b32 s2, s2, 2
	s_lshl_b64 s[4:5], s[18:19], 19
	v_readlane_b32 s10, v254, 23
	v_readlane_b32 s11, v254, 24
	s_add_u32 s20, s10, s4
	s_addc_u32 s21, s11, s5
	s_bfe_i64 s[4:5], s[2:3], 0x100000
	s_lshl_b64 s[4:5], s[4:5], 19
	v_and_b32_e32 v13, 64, v212
	s_add_u32 s24, s34, s4
	v_or_b32_e32 v154, v12, v13
	s_addc_u32 s25, s35, s5
	s_add_i32 s36, s33, 0
	v_lshl_or_b32 v0, v15, 11, v154
	s_add_i32 m0, s36, 0x10000
	v_lshl_or_b32 v2, v17, 11, v154
	s_add_i32 m0, s36, 0x12000
	v_lshl_or_b32 v4, v14, 11, v154
	s_mov_b32 m0, s36
	s_add_i32 s37, s36, 0x2000
	v_lshl_or_b32 v18, v16, 11, v154
	s_mov_b32 m0, s37
	s_add_u32 s4, s24, 0x40000
	s_addc_u32 s5, s25, 0
	s_add_i32 m0, s36, 0x14000
	v_mov_b32_e32 v1, 0
	s_add_i32 m0, s36, 0x16000
	v_mov_b32_e32 v3, v1
	s_add_u32 s4, s20, 0x40000
	s_addc_u32 s5, s21, 0
	s_add_i32 s38, s36, 0x4000
	s_mov_b32 m0, s38
	s_add_i32 s39, s36, 0x6000
	s_mov_b32 m0, s39
	v_mov_b32_e32 v5, v1
.Lp7n_join:
	v_mov_b32_e32 v19, v1
	v_lshl_add_u64 v[10:11], s[24:25], 0, v[0:1]
	s_mov_b32 s40, 0
	v_lshl_add_u64 v[8:9], s[24:25], 0, v[2:3]
	v_lshl_add_u64 v[6:7], s[20:21], 0, v[4:5]
	s_cmp_lg_u32 s3, 1
	v_lshl_add_u64 v[4:5], s[20:21], 0, v[18:19]
	s_cbranch_scc1 .LBB0_761
	s_barrier
